# static s_setprio 1 for waves 4-7 in token mixer and in the FFN-up epilogue
# baseline (speedup 1.0000x reference)
;     __device__ __forceinline__ void operator()(f32x4 (&acc)[2][2][4][2], const Unit& u, int ui, int wr, int wc, int fr_, int fq_) const {
;         int fr = fr_, fq = fq_; asm volatile("" : "+v"(fr), "+v"(fq));
; #pragma unroll
;         for (int ai = 0; ai < 2; ++ai)
; #pragma unroll
;             for (int m = 0; m < 4; ++m) { const float r = rtab[ui * 256 + ai * HALF + wr * 64 + m * 16 + fr];
; #pragma unroll
;                 for (int bj = 0; bj < 2; ++bj)
; #pragma unroll
;                     for (int n = 0; n < 2; ++n) acc[ai][bj][m][n] = acc[ai][bj][m][n] * r; }
;         const int fbase = u.pn * 128 + 32 * wc + 8 * fq;
.LBB0_1178:
	v_readfirstlane_b32 s0, v232
	s_nop 0
	s_lshr_b32 s0, s0, 6
	s_cmp_ge_u32 s0, 4
	s_cbranch_scc0 .Lprio_up_done
	s_setprio 1
